# group barrier: returning arrive atomic so the last arriver proceeds without polling; pollers no longer sleep
# speedup vs baseline: 1.0184x; 1.0029x over previous
.LBB0_588:
	s_mov_b64 s[10:11], s[84:85]
	v_mov_b32_e32 v0, v173
	s_getreg_b32 s1, hwreg(HW_REG_XCC_ID, 0, 4)
	s_waitcnt vmcnt(0)
	s_waitcnt lgkmcnt(0)
	s_barrier
	s_getreg_b32 s6, hwreg(HW_REG_HW_ID, 0, 7)
	s_and_b32 s6, s6, 63
	s_lshl_b32 s6, s6, 2
	v_mov_b32_e32 v1, s6
	ds_read_b32 v1, v1
	v_sub_u32_e32 v0, 0, v0
	s_waitcnt lgkmcnt(0)
	v_readfirstlane_b32 s6, v1
	s_lshl_b32 s6, s6, 6
	s_and_b32 s6, s6, 0x3fc0
	v_cmp_eq_u32_e32 vcc, s6, v0
	s_and_saveexec_b64 s[8:9], vcc
	s_cbranch_execz .LBB0_640
	s_load_dwordx2 s[10:11], s[10:11], 0xe0
	s_and_b32 s12, s2, 7
	s_lshl_b32 s12, s12, 3
	s_bfe_u32 s13, s2, 0x30003
	s_add_u32 s12, s12, s13
	s_lshl_b32 s12, s12, 2
	s_add_u32 s12, s12, 0xf500020
	s_add_u32 s101, s101, 4
	v_mov_b32_e32 v1, 1
	s_waitcnt vmcnt(0) lgkmcnt(0)
	s_add_u32 s10, s10, s12
	s_addc_u32 s11, s11, 0
	global_atomic_add v1, v161, v1, s[10:11] sc0
	s_waitcnt vmcnt(0)
	v_readfirstlane_b32 s12, v1
	s_add_u32 s12, s12, 1
	s_cmp_lt_u32 s12, s101
	s_cbranch_scc0 .Lgb_done_a
.Lgb_spin_a:
	global_load_dword v1, v161, s[10:11] sc1
	s_waitcnt vmcnt(0)
	v_readfirstlane_b32 s12, v1
	s_cmp_lt_u32 s12, s101
	s_cbranch_scc1 .Lgb_spin_a
.Lgb_done_a:
	buffer_inv sc1
	s_waitcnt vmcnt(0)

.LBB0_660:
	s_mov_b64 s[10:11], s[84:85]
	v_mov_b32_e32 v0, v173
	s_getreg_b32 s1, hwreg(HW_REG_XCC_ID, 0, 4)
	s_waitcnt vmcnt(0)
	s_barrier
	s_getreg_b32 s6, hwreg(HW_REG_HW_ID, 0, 7)
	s_and_b32 s6, s6, 63
	s_lshl_b32 s6, s6, 2
	v_mov_b32_e32 v1, s6
	ds_read_b32 v1, v1
	v_sub_u32_e32 v0, 0, v0
	s_waitcnt lgkmcnt(0)
	v_readfirstlane_b32 s6, v1
	s_lshl_b32 s6, s6, 6
	s_and_b32 s6, s6, 0x3fc0
	v_cmp_eq_u32_e32 vcc, s6, v0
	s_and_saveexec_b64 s[8:9], vcc
	s_cbranch_execz .LBB0_712
	s_load_dwordx2 s[10:11], s[10:11], 0xe0
	s_and_b32 s12, s2, 7
	s_lshl_b32 s12, s12, 3
	s_bfe_u32 s13, s2, 0x30003
	s_add_u32 s12, s12, s13
	s_lshl_b32 s12, s12, 2
	s_add_u32 s12, s12, 0xf500020
	s_add_u32 s101, s101, 4
	v_mov_b32_e32 v1, 1
	s_waitcnt vmcnt(0) lgkmcnt(0)
	s_add_u32 s10, s10, s12
	s_addc_u32 s11, s11, 0
	global_atomic_add v1, v161, v1, s[10:11] sc0
	s_waitcnt vmcnt(0)
	v_readfirstlane_b32 s12, v1
	s_add_u32 s12, s12, 1
	s_cmp_lt_u32 s12, s101
	s_cbranch_scc0 .Lgb_done_b
